# v210 + phase-range kernarg load (s[60:61]) also issued at kernel entry
# speedup vs baseline: 1.0015x; 1.0015x over previous
_Z6mk_fwd4Args:
	s_load_dword s33, s[0:1], 0xa8
	s_load_dwordx2 s[60:61], s[0:1], 0xa0
	s_load_dwordx16 s[12:27], s[0:1], 0x0
	s_load_dwordx16 s[36:51], s[0:1], 0x40
	s_load_dwordx8 s[52:59], s[0:1], 0x80
	s_mov_b32 s10, s2
	s_add_u32 s2, s0, 0xa8
	s_addc_u32 s3, s1, 0
	v_cmp_gt_u32_e32 vcc, 64, v0
	v_writelane_b32 v254, s2, 0
	s_nop 1
	v_writelane_b32 v254, s3, 1
	s_and_saveexec_b64 s[2:3], vcc
	v_lshl_add_u32 v1, v0, 2, 0
	v_add_u32_e32 v1, 0x25f00, v1
	v_mov_b32_e32 v2, 0
	ds_write_b32 v1, v2
	s_or_b64 exec, exec, s[2:3]
	s_waitcnt lgkmcnt(0)
	s_barrier
	s_getreg_b32 s2, hwreg(HW_REG_XCC_ID, 0, 4)
	s_and_b32 s62, s2, 15
	v_cmp_eq_u32_e64 s[96:97], 0, v0
	s_and_saveexec_b64 s[2:3], s[96:97]
	s_cbranch_execz .LBB0_5
	s_mov_b64 s[4:5], exec
	v_mbcnt_lo_u32_b32 v1, s4, 0
	v_mbcnt_hi_u32_b32 v1, s5, v1
	v_cmp_eq_u32_e32 vcc, 0, v1
	s_and_b64 s[6:7], exec, vcc
	s_mov_b64 exec, s[6:7]
	s_cbranch_execz .LBB0_5
	s_lshl_b32 s6, s62, 8
	s_bcnt1_i32_b64 s7, s[4:5]
	s_getpc_b64 s[4:5]
	s_add_u32 s4, s4, g_ctl@rel32@lo+5124
	s_addc_u32 s5, s5, g_ctl@rel32@hi+5132
	v_mov_b32_e32 v1, s6
	v_mov_b32_e32 v2, s7
	global_atomic_add v1, v2, s[4:5]
